# P0 keeps only the W_in transposes (9248 items); the sample-path workgroups take 8208 items at the end of P3
# speedup vs baseline: 1.0007x; 1.0007x over previous
; #define LAS __attribute__((address_space(3)))
; __device__ __forceinline__ int ltid() { int t = threadIdx.x; asm volatile("" : "+v"(t)); return t; }
; __device__ __forceinline__ KArgs ka_get() { KArgs p = (KArgs)__builtin_amdgcn_kernarg_segment_ptr(); asm volatile("" : "+s"(p)); return p; }
; __global__ void __launch_bounds__(512, 2) mk_fwd(Args args) {
;     ...
;     if (IN(0)) { const KArgs KA = ka_get(); const int tid = ltid(), lane = tid & 63, wave = __builtin_amdgcn_readfirstlane(tid >> 6); (void)lane; (void)wave;
;         LAS float* scr = (LAS float*)(lds + wave * 16384);
;         const int gw = bx * 8 + wave, NGW = G * 8;
;         constexpr int I_IN = (DM / 64) * (9248 / 32), I_OUT = (DMIX / 64) * (DM / 32), I_UP = (DM / 64) * (FF2 / 32), I_DN = (FF / 64) * (DM / 32);
;         constexpr int n_items0 = I_IN + I_OUT + I_UP + I_DN;
;         for (int it = gw; it < n_items0; it += NGW) {
;             int r = it;
;             if (r < I_IN) { const int nblk = 9248 / 32, kb = r / nblk, nb = r % nblk; p0_transpose_item(w_in, DM, 9248, WinT, 64 * kb, 32 * nb, win_dest_row(32 * nb), scr, lane); continue; } r -= I_IN;
.LBB0_18:
	s_cmp_lt_i32 s88, 1
	s_cselect_b64 s[0:1], -1, 0
	s_cmp_gt_i32 s89, 0
	s_cselect_b64 s[4:5], -1, 0
	s_and_b64 s[0:1], s[0:1], s[4:5]
	s_andn2_b64 vcc, exec, s[0:1]
	s_cbranch_vccnz .LBB0_61
	s_mov_b64 s[8:9], s[96:97]
	v_mov_b32_e32 v1, v212
	s_lshl_b32 s10, s94, 3
	v_readfirstlane_b32 s3, v1
	s_ashr_i32 s4, s3, 6
	s_lshl_b32 s3, s2, 3
	v_and_b32_e32 v3, 63, v1
	s_add_i32 s3, s4, s3
	s_cmpk_gt_i32 s3, 0x241f
	v_lshlrev_b32_e32 v0, 3, v3
	s_cbranch_scc1 .LBB0_54
	s_load_dwordx2 s[12:13], s[8:9], 0x38
	s_load_dwordx2 s[14:15], s[8:9], 0x90
	s_load_dwordx2 s[16:17], s[8:9], 0xa0
	s_load_dwordx2 s[18:19], s[8:9], 0xb8
	s_load_dwordx2 s[20:21], s[8:9], 0x98
	s_load_dwordx2 s[22:23], s[8:9], 0xd0
	v_lshrrev_b32_e32 v4, 3, v3
	v_and_b32_e32 v7, 7, v3
	v_lshlrev_b32_e32 v5, 4, v7
	v_lshlrev_b32_e32 v6, 5, v7
	s_lshl_b32 s24, s4, 14
	v_lshl_add_u32 v16, v4, 7, s24
	v_xor_b32_e32 v8, 0, v7
	v_lshl_add_u32 v8, v8, 4, v16
	v_xor_b32_e32 v9, 1, v7
	v_lshl_add_u32 v9, v9, 4, v16
	v_xor_b32_e32 v10, 2, v7
	v_lshl_add_u32 v10, v10, 4, v16
	v_xor_b32_e32 v11, 3, v7
	v_lshl_add_u32 v11, v11, 4, v16
	v_xor_b32_e32 v12, 4, v7
	v_lshl_add_u32 v12, v12, 4, v16
	v_xor_b32_e32 v13, 5, v7
	v_lshl_add_u32 v13, v13, 4, v16
	v_xor_b32_e32 v14, 6, v7
	v_lshl_add_u32 v14, v14, 4, v16
	v_xor_b32_e32 v15, 7, v7
	v_lshl_add_u32 v15, v15, 4, v16
	v_lshlrev_b32_e32 v20, 2, v7
	v_lshl_add_u32 v21, v7, 10, s24
	v_add_u32_e32 v16, 0, v4
	v_xor_b32_e32 v16, v16, v20
	v_lshl_add_u32 v16, v16, 2, v21
	v_add_u32_e32 v17, 8, v4
	v_xor_b32_e32 v17, v17, v20
	v_lshl_add_u32 v17, v17, 2, v21
	v_add_u32_e32 v18, 16, v4
	v_xor_b32_e32 v18, v18, v20
	v_lshl_add_u32 v18, v18, 2, v21
	v_add_u32_e32 v19, 24, v4
	v_xor_b32_e32 v19, v19, v20
	v_lshl_add_u32 v19, v19, 2, v21
	s_mov_b32 s11, s3
	s_waitcnt lgkmcnt(0)
	s_cmpk_lt_u32 s11, 9248
	s_cbranch_scc0 .Lp0t_pro_notin
	s_mul_hi_u32 s40, s11, 14861479
	s_mul_i32 s42, s40, 289
	s_sub_u32 s41, s11, s42
	s_mul_i32 s42, s40, 2367488
	s_lshl_b32 s43, s41, 7
	s_add_u32 s42, s42, s43
	s_add_u32 s26, s12, s42
	s_addc_u32 s27, s13, 0
	s_mov_b32 s28, 36992
	s_lshl_b32 s45, s41, 5
	s_mov_b32 s46, s45
	s_cmpk_lt_u32 s45, 5120
	s_cbranch_scc1 .Lp0t_pro_drow_done
	s_movk_i32 s46, 9216
	s_cmpk_lt_u32 s45, 5152
	s_cbranch_scc1 .Lp0t_pro_drow_done
	s_sub_u32 s47, s45, 5152
	s_movk_i32 s43, 5120
	s_cmpk_lt_u32 s45, 7200
	s_cbranch_scc1 .Lp0t_pro_drow_cf
	s_sub_u32 s47, s45, 7200
	s_movk_i32 s43, 5248

; __global__ void __launch_bounds__(512, 2) mk_fwd(Args args) {
;     ...
;         for (int it = gw; it < n_items0; it += NGW) {
;             int r = it;
;             if (r < I_IN) { const int nblk = 9248 / 32, kb = r / nblk, nb = r % nblk; p0_transpose_item(w_in, DM, 9248, WinT, 64 * kb, 32 * nb, win_dest_row(32 * nb), scr, lane); continue; } r -= I_IN;
.Lp0t_loop:
	s_cmpk_lt_u32 s11, 9248
	s_cbranch_scc0 .Lp0t_last
	s_cmpk_lt_u32 s11, 9248
	s_cbranch_scc0 .Lp0t_main_notin
	s_mul_hi_u32 s40, s11, 14861479
	s_mul_i32 s42, s40, 289
	s_sub_u32 s41, s11, s42
	s_mul_i32 s42, s40, 2367488
	s_lshl_b32 s43, s41, 7
	s_add_u32 s42, s42, s43
	s_add_u32 s26, s12, s42
	s_addc_u32 s27, s13, 0
	s_mov_b32 s28, 36992
	s_lshl_b32 s45, s41, 5
	s_mov_b32 s46, s45
	s_cmpk_lt_u32 s45, 5120
	s_cbranch_scc1 .Lp0t_main_drow_done
	s_movk_i32 s46, 9216
	s_cmpk_lt_u32 s45, 5152
	s_cbranch_scc1 .Lp0t_main_drow_done
	s_sub_u32 s47, s45, 5152
	s_movk_i32 s43, 5120
	s_cmpk_lt_u32 s45, 7200
	s_cbranch_scc1 .Lp0t_main_drow_cf
	s_sub_u32 s47, s45, 7200
	s_movk_i32 s43, 5248

; __device__ __forceinline__ unsigned pk2(float lo, float hi) { unsigned r; asm("v_cvt_pk_bf16_f32 %0, %1, %2" : "=v"(r) : "v"(lo), "v"(hi)); return r; }
; __device__ __forceinline__ void rms_row_to_bf16(const float* xrow, const float* w, bf16_t* orow, int lane) {
;     f32x4 v[8], ww[8]; float s = 0.f;
; #pragma unroll
;     for (int j = 0; j < 8; ++j) { v[j] = *(const f32x4*)(xrow + (j * 64 + lane) * 4); ww[j] = *(const f32x4*)(w + (j * 64 + lane) * 4); }
; #pragma unroll
;     for (int j = 0; j < 8; ++j) s += (v[j].x * v[j].x + v[j].y * v[j].y) + (v[j].z * v[j].z + v[j].w * v[j].w);
;     const float r = rsqrtf(wave_sum(s) * (1.f / DM) + EPS);
; #pragma unroll
;     for (int j = 0; j < 8; ++j) {
;         u32x2 o; o.x = pk2(v[j].x * r * ww[j].x, v[j].y * r * ww[j].y); o.y = pk2(v[j].z * r * ww[j].z, v[j].w * r * ww[j].w);
;         *(u32x2*)(orow + (j * 64 + lane) * 4) = o; }
; }
; __global__ void __launch_bounds__(512, 2) mk_fwd(Args args) {
;     ...
;         const int gr = (gw + NGW - (n_items0 % NGW)) % NGW;
;         for (int m = gr; m < MT; m += NGW) { const float* xr = (m < MP) ? x_prompt + (size_t)m * DM : x_sample + (size_t)(m - MP) * DM; rms_row_to_bf16(xr, norm_mix_w, XN + (size_t)m * DM, lane); }
.LBB0_54:
	s_abs_i32 s4, s10
	v_cvt_f32_u32_e32 v1, s4
	s_sub_i32 s5, 0, s4
	s_add_i32 s3, s3, s10
	v_rcp_iflag_f32_e32 v1, v1
	s_nop 0
	v_mul_f32_e32 v1, 0x4f7ffffe, v1
	v_cvt_u32_f32_e32 v1, v1
	s_nop 0
	v_readfirstlane_b32 s6, v1
	s_mul_i32 s5, s5, s6
	s_mul_hi_u32 s5, s6, s5
	s_add_i32 s6, s6, s5
	s_mul_hi_u32 s5, s6, 0x2420
	s_mul_i32 s5, s5, s4
	s_sub_i32 s5, 0x2420, s5
	s_sub_i32 s7, s5, s4
	s_cmp_ge_u32 s5, s4
	s_cselect_b32 s5, s7, s5
	s_sub_i32 s7, s5, s4
	s_cmp_ge_u32 s5, s4
	s_cselect_b32 s5, s7, s5
	s_sub_i32 s3, s3, s5
	s_ashr_i32 s5, s3, 31
	s_abs_i32 s3, s3
	s_mul_hi_u32 s6, s3, s6
	s_mul_i32 s6, s6, s4
	s_sub_i32 s3, s3, s6
	s_sub_i32 s6, s3, s4
	s_cmp_ge_u32 s3, s4
	s_cselect_b32 s3, s6, s3
	s_sub_i32 s6, s3, s4
	s_cmp_ge_u32 s3, s4
	s_cselect_b32 s3, s6, s3
	s_xor_b32 s3, s3, s5
	s_sub_i32 s4, s3, s5
	s_cmpk_gt_i32 s4, 0x21ff
	s_mov_b32 s7, 0
	s_cbranch_scc1 .LBB0_61
	s_load_dwordx2 s[12:13], s[8:9], 0x0
	s_load_dwordx2 s[14:15], s[8:9], 0x8
	s_load_dwordx2 s[16:17], s[8:9], 0x30
	s_load_dwordx2 s[18:19], s[8:9], 0xd0
	v_lshlrev_b32_e32 v4, 4, v3
	v_lshlrev_b32_e32 v5, 3, v3
	v_xor_b32_e32 v6, 1, v3
	v_lshlrev_b32_e32 v6, 2, v6
	v_xor_b32_e32 v7, 2, v3
	v_lshlrev_b32_e32 v7, 2, v7
	v_xor_b32_e32 v8, 4, v3
	v_lshlrev_b32_e32 v8, 2, v8
	v_xor_b32_e32 v9, 8, v3
	v_lshlrev_b32_e32 v9, 2, v9
	v_xor_b32_e32 v10, 16, v3
	v_lshlrev_b32_e32 v10, 2, v10
	v_xor_b32_e32 v11, 32, v3
	v_lshlrev_b32_e32 v11, 2, v11
	v_mov_b32_e32 v16, 0x3727c5ac
	s_waitcnt lgkmcnt(0)
	s_add_u32 s18, s18, 0x7580000
	s_addc_u32 s19, s19, 0
	global_load_dwordx4 v[40:43], v4, s[16:17] offset:0
	global_load_dwordx4 v[44:47], v4, s[16:17] offset:1024
	global_load_dwordx4 v[48:51], v4, s[16:17] offset:2048
	global_load_dwordx4 v[52:55], v4, s[16:17] offset:3072
	s_add_u32 s16, s16, 4096
	s_addc_u32 s17, s17, 0
	global_load_dwordx4 v[56:59], v4, s[16:17] offset:0
	global_load_dwordx4 v[60:63], v4, s[16:17] offset:1024
	global_load_dwordx4 v[64:67], v4, s[16:17] offset:2048
	global_load_dwordx4 v[68:71], v4, s[16:17] offset:3072
	s_cmpk_lt_u32 s4, 8192
	s_cselect_b32 s20, s12, s14
	s_cselect_b32 s21, s13, s15
	s_cselect_b32 s28, 0, 8192
	s_sub_u32 s28, s4, s28
	s_lshr_b32 s29, s28, 19
	s_lshl_b32 s28, s28, 13
	s_add_u32 s20, s20, s28
	s_addc_u32 s21, s21, s29
	global_load_dwordx4 v[72:75], v4, s[20:21] offset:0 nt
	global_load_dwordx4 v[76:79], v4, s[20:21] offset:1024 nt
	global_load_dwordx4 v[80:83], v4, s[20:21] offset:2048 nt
	global_load_dwordx4 v[84:87], v4, s[20:21] offset:3072 nt
	s_add_u32 s20, s20, 4096
	s_addc_u32 s21, s21, 0
	global_load_dwordx4 v[88:91], v4, s[20:21] offset:0 nt
	global_load_dwordx4 v[92:95], v4, s[20:21] offset:1024 nt
	global_load_dwordx4 v[96:99], v4, s[20:21] offset:2048 nt
	global_load_dwordx4 v[100:103], v4, s[20:21] offset:3072 nt
	s_mov_b32 s27, 0

; #define LAS __attribute__((address_space(3)))
; __device__ __forceinline__ void p0_transpose_item(const float* W, int K, int N, bf16_t* WT, int k0, int n0, int drow0, LAS float* scr, int lane, const float* kscale = nullptr) {
;     const float ks = kscale ? kscale[k0 + lane] : 1.f;
; #pragma unroll 8
;     for (int i = 0; i < 32; ++i) { const int kk = 2 * i + (lane >> 5); scr[kk * 33 + (lane & 31)] = W[(size_t)(k0 + kk) * N + n0 + (lane & 31)] * __shfl(ks, kk); }
;     asm volatile("s_waitcnt lgkmcnt(0)" ::: "memory");
;     const int c = lane & 7;
; #pragma unroll
;     for (int j = 0; j < 4; ++j) { const int n = (lane >> 3) + 8 * j; const LAS float* s = scr + (8 * c) * 33 + n;
;         u32x4 o; o.x = pk2(s[0 * 33], s[1 * 33]); o.y = pk2(s[2 * 33], s[3 * 33]); o.z = pk2(s[4 * 33], s[5 * 33]); o.w = pk2(s[6 * 33], s[7 * 33]);
;         *(u32x4*)(WT + (size_t)(drow0 + n) * K + k0 + 8 * c) = o; }
;     asm volatile("s_waitcnt lgkmcnt(0)" ::: "memory");
; }
; __device__ __forceinline__ int win_dest_row(int n0) {
;     if (n0 < 5120) return n0;
;     if (n0 < 5152) return CDT + (n0 - 5120);
;     if (n0 < 7200) { const int c = n0 - 5152; return CCF + 256 * (c >> 7) + (c & 127); }
;     { const int c = n0 - 7200; return CCF + 256 * (c >> 7) + 128 + (c & 127); }
; __global__ void __launch_bounds__(512, 2) mk_fwd(Args args) {
;     ...
;         constexpr int I_IN = (DM / 64) * (9248 / 32), I_OUT = (DMIX / 64) * (DM / 32), I_UP = (DM / 64) * (FF2 / 32), I_DN = (FF / 64) * (DM / 32);
;         constexpr int n_items0 = I_IN + I_OUT + I_UP + I_DN;
;         for (int it = gw; it < n_items0; it += NGW) {
;             int r = it;
;             if (r < I_IN) { const int nblk = 9248 / 32, kb = r / nblk, nb = r % nblk; p0_transpose_item(w_in, DM, 9248, WinT, 64 * kb, 32 * nb, win_dest_row(32 * nb), scr, lane); continue; } r -= I_IN;
;             if (r < I_OUT) { const int nblk = DM / 32, kb = r / nblk, nb = r % nblk; p0_transpose_item(w_out, DMIX, DM, WoutT, 64 * kb, 32 * nb, 32 * nb, scr, lane); continue; } r -= I_OUT;
;             if (r < I_UP) { const int nblk = FF2 / 32, kb = r / nblk, nb = r % nblk; p0_transpose_item(w_up, DM, FF2, WupT, 64 * kb, 32 * nb, 32 * nb, scr, lane, norm_ffn_w); continue; } r -= I_UP;
;             { const int nblk = DM / 32, kb = r / nblk, nb = r % nblk; p0_transpose_item(w_down, FF, DM, WdnT, 64 * kb, 32 * nb, 32 * nb, scr, lane); }
.LBB0_491:
	v_writelane_b32 v254, s3, 0
	v_writelane_b32 v254, s4, 1
	v_writelane_b32 v254, s8, 2
	v_writelane_b32 v254, s9, 3
	v_writelane_b32 v254, s10, 4
	v_writelane_b32 v254, s11, 5
	v_writelane_b32 v254, s12, 6
	v_writelane_b32 v254, s13, 7
	v_writelane_b32 v254, s14, 8
	v_writelane_b32 v254, s15, 9
	v_writelane_b32 v254, s16, 10
	v_writelane_b32 v254, s17, 11
	v_writelane_b32 v254, s18, 12
	v_writelane_b32 v254, s19, 13
	v_writelane_b32 v254, s20, 14
	v_writelane_b32 v254, s21, 15
	v_writelane_b32 v254, s22, 16
	v_writelane_b32 v254, s23, 17
	v_writelane_b32 v254, s24, 18
	v_writelane_b32 v254, s25, 19
	v_writelane_b32 v254, s26, 20
	v_writelane_b32 v254, s27, 21
	v_writelane_b32 v254, s28, 22
	v_writelane_b32 v254, s29, 23
	v_writelane_b32 v254, s30, 24
	v_writelane_b32 v254, s31, 25
	v_writelane_b32 v254, s32, 26
	v_writelane_b32 v254, s33, 27
	v_writelane_b32 v254, s34, 28
	v_writelane_b32 v254, s35, 29
	v_writelane_b32 v254, s36, 30
	v_writelane_b32 v254, s37, 31
	v_writelane_b32 v254, s38, 32
	v_writelane_b32 v254, s39, 33
	v_writelane_b32 v254, s40, 34
	v_writelane_b32 v254, s41, 35
	v_writelane_b32 v254, s42, 36
	v_writelane_b32 v254, s43, 37
	v_writelane_b32 v254, s44, 38
	v_writelane_b32 v254, s45, 39
	v_writelane_b32 v254, s46, 40
	v_writelane_b32 v254, s47, 41
	v_writelane_b32 v254, s48, 42
	v_writelane_b32 v254, s49, 43
	v_writelane_b32 v254, s50, 44
	v_writelane_b32 v254, s51, 45
	v_writelane_b32 v254, s52, 46
	v_writelane_b32 v254, s53, 47
	v_writelane_b32 v254, s54, 48
	v_writelane_b32 v254, s55, 49
	s_cmpk_lt_u32 s2, 128
	s_cbranch_scc1 .Ltup3_skip
	s_mov_b64 s[8:9], s[96:97]
	v_and_b32_e32 v3, 63, v212
	v_readfirstlane_b32 s4, v212
	s_sub_u32 s3, s2, 128
	s_lshl_b32 s3, s3, 3
	s_lshr_b32 s4, s4, 6
	s_add_u32 s3, s3, s4
	s_add_u32 s11, s3, 9248
	s_sub_u32 s10, s94, 128
	s_lshl_b32 s10, s10, 3
	s_cmpk_lt_u32 s11, 17456
	s_cbranch_scc0 .Ltup3_skip
	s_load_dwordx2 s[12:13], s[8:9], 0x38
	s_load_dwordx2 s[14:15], s[8:9], 0x90
	s_load_dwordx2 s[16:17], s[8:9], 0xa0
	s_load_dwordx2 s[18:19], s[8:9], 0xb8
	s_load_dwordx2 s[20:21], s[8:9], 0x98
	s_load_dwordx2 s[22:23], s[8:9], 0xd0
	v_lshrrev_b32_e32 v4, 3, v3
	v_and_b32_e32 v7, 7, v3
	v_lshlrev_b32_e32 v5, 4, v7
	v_lshlrev_b32_e32 v6, 5, v7
	s_lshl_b32 s24, s4, 14
	v_lshl_add_u32 v16, v4, 7, s24
	v_xor_b32_e32 v8, 0, v7
	v_lshl_add_u32 v8, v8, 4, v16
	v_xor_b32_e32 v9, 1, v7
	v_lshl_add_u32 v9, v9, 4, v16
	v_xor_b32_e32 v10, 2, v7
	v_lshl_add_u32 v10, v10, 4, v16
	v_xor_b32_e32 v11, 3, v7
	v_lshl_add_u32 v11, v11, 4, v16
	v_xor_b32_e32 v12, 4, v7
	v_lshl_add_u32 v12, v12, 4, v16
	v_xor_b32_e32 v13, 5, v7
	v_lshl_add_u32 v13, v13, 4, v16
	v_xor_b32_e32 v14, 6, v7
	v_lshl_add_u32 v14, v14, 4, v16
	v_xor_b32_e32 v15, 7, v7
	v_lshl_add_u32 v15, v15, 4, v16
	v_lshlrev_b32_e32 v20, 2, v7
	v_lshl_add_u32 v21, v7, 10, s24
	v_add_u32_e32 v16, 0, v4
	v_xor_b32_e32 v16, v16, v20
	v_lshl_add_u32 v16, v16, 2, v21
	v_add_u32_e32 v17, 8, v4
	v_xor_b32_e32 v17, v17, v20
	v_lshl_add_u32 v17, v17, 2, v21
	v_add_u32_e32 v18, 16, v4
	v_xor_b32_e32 v18, v18, v20
	v_lshl_add_u32 v18, v18, 2, v21
	v_add_u32_e32 v19, 24, v4
	v_xor_b32_e32 v19, v19, v20
	v_lshl_add_u32 v19, v19, 2, v21
	s_waitcnt lgkmcnt(0)
	s_cmpk_lt_u32 s11, 9248
	s_cbranch_scc0 .Ltup3_pro_notin
	s_mul_hi_u32 s40, s11, 14861479
	s_mul_i32 s42, s40, 289
	s_sub_u32 s41, s11, s42
	s_mul_i32 s42, s40, 2367488
	s_lshl_b32 s43, s41, 7
	s_add_u32 s42, s42, s43
	s_add_u32 s26, s12, s42
	s_addc_u32 s27, s13, 0
	s_mov_b32 s28, 36992
	s_lshl_b32 s45, s41, 5
	s_mov_b32 s46, s45
	s_cmpk_lt_u32 s45, 5120
	s_cbranch_scc1 .Ltup3_pro_drow_done
	s_movk_i32 s46, 9216
	s_cmpk_lt_u32 s45, 5152
	s_cbranch_scc1 .Ltup3_pro_drow_done
	s_sub_u32 s47, s45, 5152
	s_movk_i32 s43, 5120
	s_cmpk_lt_u32 s45, 7200
	s_cbranch_scc1 .Ltup3_pro_drow_cf
	s_sub_u32 s47, s45, 7200
	s_movk_i32 s43, 5248
